# down GEMM prompt epilogue: all 16 residual loads issued up front and consumed with counted waits instead of a load/wait/store ladder
# speedup vs baseline: 1.0018x; 1.0018x over previous
.LBB0_1759:
	v_lshl_add_u32 v150, s30, 8, v138
	v_lshl_or_b32 v148, s28, 8, v139
	v_ashrrev_i32_e32 v151, 31, v150
	v_ashrrev_i32_e32 v149, 31, v148
	v_lshlrev_b64 v[152:153], 12, v[150:151]
	v_lshlrev_b64 v[158:159], 1, v[148:149]
	v_lshl_add_u64 v[152:153], s[10:11], 0, v[152:153]
	v_lshl_add_u64 v[152:153], v[152:153], 0, v[158:159]
	v_lshlrev_b64 v[160:161], 13, v[150:151]
	v_lshlrev_b64 v[162:163], 2, v[148:149]
	v_lshl_add_u64 v[160:161], s[92:93], 0, v[160:161]
	v_lshl_add_u64 v[160:161], v[160:161], 0, v[162:163]
	global_load_dwordx4 v[168:171], v[152:153], off
	global_load_dwordx4 v[172:175], v[152:153], off offset:256
	s_mov_b32 s34, 0x10000
	s_mov_b32 s35, 0
	v_lshl_add_u64 v[148:149], v[152:153], 0, s[34:35]
	global_load_dwordx4 v[176:179], v[148:149], off
	global_load_dwordx4 v[180:183], v[148:149], off offset:256
	s_mov_b32 s34, 0x20000
	s_mov_b32 s35, 0
	v_lshl_add_u64 v[148:149], v[152:153], 0, s[34:35]
	global_load_dwordx4 v[184:187], v[148:149], off
	global_load_dwordx4 v[188:191], v[148:149], off offset:256
	s_mov_b32 s34, 0x30000
	s_mov_b32 s35, 0
	v_lshl_add_u64 v[148:149], v[152:153], 0, s[34:35]
	global_load_dwordx4 v[192:195], v[148:149], off
	global_load_dwordx4 v[196:199], v[148:149], off offset:256
	s_mov_b32 s34, 0x80000
	s_mov_b32 s35, 0
	v_lshl_add_u64 v[148:149], v[152:153], 0, s[34:35]
	global_load_dwordx4 v[200:203], v[148:149], off
	global_load_dwordx4 v[204:207], v[148:149], off offset:256
	s_mov_b32 s34, 0x90000
	s_mov_b32 s35, 0
	v_lshl_add_u64 v[148:149], v[152:153], 0, s[34:35]
	global_load_dwordx4 v[208:211], v[148:149], off
	global_load_dwordx4 v[212:215], v[148:149], off offset:256
	s_mov_b32 s34, 0xa0000
	s_mov_b32 s35, 0
	v_lshl_add_u64 v[148:149], v[152:153], 0, s[34:35]
	global_load_dwordx4 v[216:219], v[148:149], off
	global_load_dwordx4 v[220:223], v[148:149], off offset:256
	s_mov_b32 s34, 0xb0000
	s_mov_b32 s35, 0
	v_lshl_add_u64 v[148:149], v[152:153], 0, s[34:35]
	global_load_dwordx4 v[224:227], v[148:149], off
	global_load_dwordx4 v[228:231], v[148:149], off offset:256
	s_waitcnt vmcnt(15)
	v_lshlrev_b32_e32 v232, 16, v168
	v_and_b32_e32 v233, 0xffff0000, v168
	v_lshlrev_b32_e32 v234, 16, v169
	v_and_b32_e32 v235, 0xffff0000, v169
	v_lshlrev_b32_e32 v236, 16, v170
	v_and_b32_e32 v237, 0xffff0000, v170
	v_lshlrev_b32_e32 v158, 16, v171
	v_and_b32_e32 v159, 0xffff0000, v171
	v_pk_fma_f32 v[124:125], v[232:233], s[16:17], v[124:125] op_sel_hi:[1,0,1]
	v_pk_fma_f32 v[126:127], v[234:235], s[16:17], v[126:127] op_sel_hi:[1,0,1]
	v_pk_fma_f32 v[120:121], v[236:237], s[16:17], v[120:121] op_sel_hi:[1,0,1]
	v_pk_fma_f32 v[122:123], v[158:159], s[16:17], v[122:123] op_sel_hi:[1,0,1]
	global_store_dwordx4 v[160:161], v[124:127], off
	global_store_dwordx4 v[160:161], v[120:123], off offset:16
	s_waitcnt vmcnt(16)
	v_lshlrev_b32_e32 v232, 16, v172
	v_and_b32_e32 v233, 0xffff0000, v172
	v_lshlrev_b32_e32 v234, 16, v173
	v_and_b32_e32 v235, 0xffff0000, v173
	v_lshlrev_b32_e32 v236, 16, v174
	v_and_b32_e32 v237, 0xffff0000, v174
	v_lshlrev_b32_e32 v158, 16, v175
	v_and_b32_e32 v159, 0xffff0000, v175
	v_pk_fma_f32 v[116:117], v[232:233], s[16:17], v[116:117] op_sel_hi:[1,0,1]
	v_pk_fma_f32 v[118:119], v[234:235], s[16:17], v[118:119] op_sel_hi:[1,0,1]
	v_pk_fma_f32 v[112:113], v[236:237], s[16:17], v[112:113] op_sel_hi:[1,0,1]
	v_pk_fma_f32 v[114:115], v[158:159], s[16:17], v[114:115] op_sel_hi:[1,0,1]
	global_store_dwordx4 v[160:161], v[116:119], off offset:512
	global_store_dwordx4 v[160:161], v[112:115], off offset:528
	s_mov_b32 s34, 0x20000
	s_mov_b32 s35, 0
	v_lshl_add_u64 v[148:149], v[160:161], 0, s[34:35]
	s_waitcnt vmcnt(17)
	v_lshlrev_b32_e32 v232, 16, v176
	v_and_b32_e32 v233, 0xffff0000, v176
	v_lshlrev_b32_e32 v234, 16, v177
	v_and_b32_e32 v235, 0xffff0000, v177
	v_lshlrev_b32_e32 v236, 16, v178
	v_and_b32_e32 v237, 0xffff0000, v178
	v_lshlrev_b32_e32 v158, 16, v179
	v_and_b32_e32 v159, 0xffff0000, v179
	v_pk_fma_f32 v[108:109], v[232:233], s[16:17], v[108:109] op_sel_hi:[1,0,1]
	v_pk_fma_f32 v[110:111], v[234:235], s[16:17], v[110:111] op_sel_hi:[1,0,1]
	v_pk_fma_f32 v[104:105], v[236:237], s[16:17], v[104:105] op_sel_hi:[1,0,1]
	v_pk_fma_f32 v[106:107], v[158:159], s[16:17], v[106:107] op_sel_hi:[1,0,1]
	global_store_dwordx4 v[148:149], v[108:111], off
	global_store_dwordx4 v[148:149], v[104:107], off offset:16
	s_waitcnt vmcnt(18)
	v_lshlrev_b32_e32 v232, 16, v180
	v_and_b32_e32 v233, 0xffff0000, v180
	v_lshlrev_b32_e32 v234, 16, v181
	v_and_b32_e32 v235, 0xffff0000, v181
	v_lshlrev_b32_e32 v236, 16, v182
	v_and_b32_e32 v237, 0xffff0000, v182
	v_lshlrev_b32_e32 v158, 16, v183
	v_and_b32_e32 v159, 0xffff0000, v183
	v_pk_fma_f32 v[100:101], v[232:233], s[16:17], v[100:101] op_sel_hi:[1,0,1]
	v_pk_fma_f32 v[102:103], v[234:235], s[16:17], v[102:103] op_sel_hi:[1,0,1]
	v_pk_fma_f32 v[96:97], v[236:237], s[16:17], v[96:97] op_sel_hi:[1,0,1]
	v_pk_fma_f32 v[98:99], v[158:159], s[16:17], v[98:99] op_sel_hi:[1,0,1]
	global_store_dwordx4 v[148:149], v[100:103], off offset:512
	global_store_dwordx4 v[148:149], v[96:99], off offset:528
	s_mov_b32 s34, 0x40000
	s_mov_b32 s35, 0
	v_lshl_add_u64 v[148:149], v[160:161], 0, s[34:35]
	s_waitcnt vmcnt(19)
	v_lshlrev_b32_e32 v232, 16, v184
	v_and_b32_e32 v233, 0xffff0000, v184
	v_lshlrev_b32_e32 v234, 16, v185
	v_and_b32_e32 v235, 0xffff0000, v185
	v_lshlrev_b32_e32 v236, 16, v186
	v_and_b32_e32 v237, 0xffff0000, v186
	v_lshlrev_b32_e32 v158, 16, v187
	v_and_b32_e32 v159, 0xffff0000, v187
	v_pk_fma_f32 v[92:93], v[232:233], s[16:17], v[92:93] op_sel_hi:[1,0,1]
	v_pk_fma_f32 v[94:95], v[234:235], s[16:17], v[94:95] op_sel_hi:[1,0,1]
	v_pk_fma_f32 v[88:89], v[236:237], s[16:17], v[88:89] op_sel_hi:[1,0,1]
	v_pk_fma_f32 v[90:91], v[158:159], s[16:17], v[90:91] op_sel_hi:[1,0,1]
	global_store_dwordx4 v[148:149], v[92:95], off
	global_store_dwordx4 v[148:149], v[88:91], off offset:16
	s_waitcnt vmcnt(20)
	v_lshlrev_b32_e32 v232, 16, v188
	v_and_b32_e32 v233, 0xffff0000, v188
	v_lshlrev_b32_e32 v234, 16, v189
	v_and_b32_e32 v235, 0xffff0000, v189
	v_lshlrev_b32_e32 v236, 16, v190
	v_and_b32_e32 v237, 0xffff0000, v190
	v_lshlrev_b32_e32 v158, 16, v191
	v_and_b32_e32 v159, 0xffff0000, v191
	v_pk_fma_f32 v[84:85], v[232:233], s[16:17], v[84:85] op_sel_hi:[1,0,1]
	v_pk_fma_f32 v[86:87], v[234:235], s[16:17], v[86:87] op_sel_hi:[1,0,1]
	v_pk_fma_f32 v[80:81], v[236:237], s[16:17], v[80:81] op_sel_hi:[1,0,1]
	v_pk_fma_f32 v[82:83], v[158:159], s[16:17], v[82:83] op_sel_hi:[1,0,1]
	global_store_dwordx4 v[148:149], v[84:87], off offset:512
	global_store_dwordx4 v[148:149], v[80:83], off offset:528
	s_mov_b32 s34, 0x60000
	s_mov_b32 s35, 0
	v_lshl_add_u64 v[148:149], v[160:161], 0, s[34:35]
	s_waitcnt vmcnt(21)
	v_lshlrev_b32_e32 v232, 16, v192
	v_and_b32_e32 v233, 0xffff0000, v192
	v_lshlrev_b32_e32 v234, 16, v193
	v_and_b32_e32 v235, 0xffff0000, v193
	v_lshlrev_b32_e32 v236, 16, v194
	v_and_b32_e32 v237, 0xffff0000, v194
	v_lshlrev_b32_e32 v158, 16, v195
	v_and_b32_e32 v159, 0xffff0000, v195
	v_pk_fma_f32 v[76:77], v[232:233], s[16:17], v[76:77] op_sel_hi:[1,0,1]
	v_pk_fma_f32 v[78:79], v[234:235], s[16:17], v[78:79] op_sel_hi:[1,0,1]
	v_pk_fma_f32 v[72:73], v[236:237], s[16:17], v[72:73] op_sel_hi:[1,0,1]
	v_pk_fma_f32 v[74:75], v[158:159], s[16:17], v[74:75] op_sel_hi:[1,0,1]
	global_store_dwordx4 v[148:149], v[76:79], off
	global_store_dwordx4 v[148:149], v[72:75], off offset:16
	s_waitcnt vmcnt(22)
	v_lshlrev_b32_e32 v232, 16, v196
	v_and_b32_e32 v233, 0xffff0000, v196
	v_lshlrev_b32_e32 v234, 16, v197
	v_and_b32_e32 v235, 0xffff0000, v197
	v_lshlrev_b32_e32 v236, 16, v198
	v_and_b32_e32 v237, 0xffff0000, v198
	v_lshlrev_b32_e32 v158, 16, v199
	v_and_b32_e32 v159, 0xffff0000, v199
	v_pk_fma_f32 v[68:69], v[232:233], s[16:17], v[68:69] op_sel_hi:[1,0,1]
	v_pk_fma_f32 v[70:71], v[234:235], s[16:17], v[70:71] op_sel_hi:[1,0,1]
	v_pk_fma_f32 v[64:65], v[236:237], s[16:17], v[64:65] op_sel_hi:[1,0,1]
	v_pk_fma_f32 v[66:67], v[158:159], s[16:17], v[66:67] op_sel_hi:[1,0,1]
	global_store_dwordx4 v[148:149], v[68:71], off offset:512
	global_store_dwordx4 v[148:149], v[64:67], off offset:528
	s_mov_b32 s34, 0x100000
	s_mov_b32 s35, 0
	v_lshl_add_u64 v[148:149], v[160:161], 0, s[34:35]
	s_waitcnt vmcnt(23)
	v_lshlrev_b32_e32 v232, 16, v200
	v_and_b32_e32 v233, 0xffff0000, v200
	v_lshlrev_b32_e32 v234, 16, v201
	v_and_b32_e32 v235, 0xffff0000, v201
	v_lshlrev_b32_e32 v236, 16, v202
	v_and_b32_e32 v237, 0xffff0000, v202
	v_lshlrev_b32_e32 v158, 16, v203
	v_and_b32_e32 v159, 0xffff0000, v203
	v_pk_fma_f32 v[60:61], v[232:233], s[16:17], v[60:61] op_sel_hi:[1,0,1]
	v_pk_fma_f32 v[62:63], v[234:235], s[16:17], v[62:63] op_sel_hi:[1,0,1]
	v_pk_fma_f32 v[56:57], v[236:237], s[16:17], v[56:57] op_sel_hi:[1,0,1]
	v_pk_fma_f32 v[58:59], v[158:159], s[16:17], v[58:59] op_sel_hi:[1,0,1]
	global_store_dwordx4 v[148:149], v[60:63], off
	global_store_dwordx4 v[148:149], v[56:59], off offset:16
	s_waitcnt vmcnt(24)
	v_lshlrev_b32_e32 v232, 16, v204
	v_and_b32_e32 v233, 0xffff0000, v204
	v_lshlrev_b32_e32 v234, 16, v205
	v_and_b32_e32 v235, 0xffff0000, v205
	v_lshlrev_b32_e32 v236, 16, v206
	v_and_b32_e32 v237, 0xffff0000, v206
	v_lshlrev_b32_e32 v158, 16, v207
	v_and_b32_e32 v159, 0xffff0000, v207
	v_pk_fma_f32 v[52:53], v[232:233], s[16:17], v[52:53] op_sel_hi:[1,0,1]
	v_pk_fma_f32 v[54:55], v[234:235], s[16:17], v[54:55] op_sel_hi:[1,0,1]
	v_pk_fma_f32 v[48:49], v[236:237], s[16:17], v[48:49] op_sel_hi:[1,0,1]
	v_pk_fma_f32 v[50:51], v[158:159], s[16:17], v[50:51] op_sel_hi:[1,0,1]
	global_store_dwordx4 v[148:149], v[52:55], off offset:512
	global_store_dwordx4 v[148:149], v[48:51], off offset:528
	s_mov_b32 s34, 0x120000
	s_mov_b32 s35, 0
	v_lshl_add_u64 v[148:149], v[160:161], 0, s[34:35]
	s_waitcnt vmcnt(25)
	v_lshlrev_b32_e32 v232, 16, v208
	v_and_b32_e32 v233, 0xffff0000, v208
	v_lshlrev_b32_e32 v234, 16, v209
	v_and_b32_e32 v235, 0xffff0000, v209
	v_lshlrev_b32_e32 v236, 16, v210
	v_and_b32_e32 v237, 0xffff0000, v210
	v_lshlrev_b32_e32 v158, 16, v211
	v_and_b32_e32 v159, 0xffff0000, v211
	v_pk_fma_f32 v[44:45], v[232:233], s[16:17], v[44:45] op_sel_hi:[1,0,1]
	v_pk_fma_f32 v[46:47], v[234:235], s[16:17], v[46:47] op_sel_hi:[1,0,1]
	v_pk_fma_f32 v[40:41], v[236:237], s[16:17], v[40:41] op_sel_hi:[1,0,1]
	v_pk_fma_f32 v[42:43], v[158:159], s[16:17], v[42:43] op_sel_hi:[1,0,1]
	global_store_dwordx4 v[148:149], v[44:47], off
	global_store_dwordx4 v[148:149], v[40:43], off offset:16
	s_waitcnt vmcnt(26)
	v_lshlrev_b32_e32 v232, 16, v212
	v_and_b32_e32 v233, 0xffff0000, v212
	v_lshlrev_b32_e32 v234, 16, v213
	v_and_b32_e32 v235, 0xffff0000, v213
	v_lshlrev_b32_e32 v236, 16, v214
	v_and_b32_e32 v237, 0xffff0000, v214
	v_lshlrev_b32_e32 v158, 16, v215
	v_and_b32_e32 v159, 0xffff0000, v215
	v_pk_fma_f32 v[36:37], v[232:233], s[16:17], v[36:37] op_sel_hi:[1,0,1]
	v_pk_fma_f32 v[38:39], v[234:235], s[16:17], v[38:39] op_sel_hi:[1,0,1]
	v_pk_fma_f32 v[32:33], v[236:237], s[16:17], v[32:33] op_sel_hi:[1,0,1]
	v_pk_fma_f32 v[34:35], v[158:159], s[16:17], v[34:35] op_sel_hi:[1,0,1]
	global_store_dwordx4 v[148:149], v[36:39], off offset:512
	global_store_dwordx4 v[148:149], v[32:35], off offset:528
	s_mov_b32 s34, 0x140000
	s_mov_b32 s35, 0
	v_lshl_add_u64 v[148:149], v[160:161], 0, s[34:35]
	s_waitcnt vmcnt(27)
	v_lshlrev_b32_e32 v232, 16, v216
	v_and_b32_e32 v233, 0xffff0000, v216
	v_lshlrev_b32_e32 v234, 16, v217
	v_and_b32_e32 v235, 0xffff0000, v217
	v_lshlrev_b32_e32 v236, 16, v218
	v_and_b32_e32 v237, 0xffff0000, v218
	v_lshlrev_b32_e32 v158, 16, v219
	v_and_b32_e32 v159, 0xffff0000, v219
	v_pk_fma_f32 v[28:29], v[232:233], s[16:17], v[28:29] op_sel_hi:[1,0,1]
	v_pk_fma_f32 v[30:31], v[234:235], s[16:17], v[30:31] op_sel_hi:[1,0,1]
	v_pk_fma_f32 v[24:25], v[236:237], s[16:17], v[24:25] op_sel_hi:[1,0,1]
	v_pk_fma_f32 v[26:27], v[158:159], s[16:17], v[26:27] op_sel_hi:[1,0,1]
	global_store_dwordx4 v[148:149], v[28:31], off
	global_store_dwordx4 v[148:149], v[24:27], off offset:16
	s_waitcnt vmcnt(28)
	v_lshlrev_b32_e32 v232, 16, v220
	v_and_b32_e32 v233, 0xffff0000, v220
	v_lshlrev_b32_e32 v234, 16, v221
	v_and_b32_e32 v235, 0xffff0000, v221
	v_lshlrev_b32_e32 v236, 16, v222
	v_and_b32_e32 v237, 0xffff0000, v222
	v_lshlrev_b32_e32 v158, 16, v223
	v_and_b32_e32 v159, 0xffff0000, v223
	v_pk_fma_f32 v[20:21], v[232:233], s[16:17], v[20:21] op_sel_hi:[1,0,1]
	v_pk_fma_f32 v[22:23], v[234:235], s[16:17], v[22:23] op_sel_hi:[1,0,1]
	v_pk_fma_f32 v[16:17], v[236:237], s[16:17], v[16:17] op_sel_hi:[1,0,1]
	v_pk_fma_f32 v[18:19], v[158:159], s[16:17], v[18:19] op_sel_hi:[1,0,1]
	global_store_dwordx4 v[148:149], v[20:23], off offset:512
	global_store_dwordx4 v[148:149], v[16:19], off offset:528
	s_mov_b32 s34, 0x160000
	s_mov_b32 s35, 0
	v_lshl_add_u64 v[148:149], v[160:161], 0, s[34:35]
	s_waitcnt vmcnt(29)
	v_lshlrev_b32_e32 v232, 16, v224
	v_and_b32_e32 v233, 0xffff0000, v224
	v_lshlrev_b32_e32 v234, 16, v225
	v_and_b32_e32 v235, 0xffff0000, v225
	v_lshlrev_b32_e32 v236, 16, v226
	v_and_b32_e32 v237, 0xffff0000, v226
	v_lshlrev_b32_e32 v158, 16, v227
	v_and_b32_e32 v159, 0xffff0000, v227
	v_pk_fma_f32 v[12:13], v[232:233], s[16:17], v[12:13] op_sel_hi:[1,0,1]
	v_pk_fma_f32 v[14:15], v[234:235], s[16:17], v[14:15] op_sel_hi:[1,0,1]
	v_pk_fma_f32 v[8:9], v[236:237], s[16:17], v[8:9] op_sel_hi:[1,0,1]
	v_pk_fma_f32 v[10:11], v[158:159], s[16:17], v[10:11] op_sel_hi:[1,0,1]
	global_store_dwordx4 v[148:149], v[12:15], off
	global_store_dwordx4 v[148:149], v[8:11], off offset:16
	s_waitcnt vmcnt(30)
	v_lshlrev_b32_e32 v232, 16, v228
	v_and_b32_e32 v233, 0xffff0000, v228
	v_lshlrev_b32_e32 v234, 16, v229
	v_and_b32_e32 v235, 0xffff0000, v229
	v_lshlrev_b32_e32 v236, 16, v230
	v_and_b32_e32 v237, 0xffff0000, v230
	v_lshlrev_b32_e32 v158, 16, v231
	v_and_b32_e32 v159, 0xffff0000, v231
	v_pk_fma_f32 v[4:5], v[232:233], s[16:17], v[4:5] op_sel_hi:[1,0,1]
	v_pk_fma_f32 v[6:7], v[234:235], s[16:17], v[6:7] op_sel_hi:[1,0,1]
	v_pk_fma_f32 v[0:1], v[236:237], s[16:17], v[0:1] op_sel_hi:[1,0,1]
	v_pk_fma_f32 v[2:3], v[158:159], s[16:17], v[2:3] op_sel_hi:[1,0,1]
	global_store_dwordx4 v[148:149], v[4:7], off offset:512
	global_store_dwordx4 v[148:149], v[0:3], off offset:528
